# v10 + flattened grid-barrier release + RWKV chunk-local block inverses on the matrix cores (waves 0-3, one 16x16 block each, (I-L)(I+L^2)(I+L^4)(I+L^8) with bf16 16x16x16 MFMA, f32 accumulate); split
# speedup vs baseline: 1.1001x; 1.0029x over previous
.LBB0_389:
	s_andn2_b64 vcc, exec, s[8:9]
	s_nop 6
	ds_write2_b32 v26, v66, v67 offset0:16 offset1:88
	ds_write2_b32 v26, v68, v69 offset0:160 offset1:232
	v_readfirstlane_b32 s26, v0
	s_lshr_b32 s26, s26, 6
	s_cmp_gt_u32 s26, 3
	s_cbranch_scc1 .LBB0_391
	s_mul_i32 s27, s26, 0xa20
	v_and_b32_e32 v28, 63, v0
	v_and_b32_e32 v166, 15, v28
	v_lshrrev_b32_e32 v173, 4, v28
	v_mul_u32_u24_e32 v186, 0xa0, v166
	v_lshl_add_u32 v186, v173, 3, v186
	v_add_u32_e32 v186, s27, v186
	ds_read_b64 v[26:27], v186
	v_lshrrev_b32_e32 v188, 2, v166
	v_lshl_add_u32 v188, v173, 2, v188
	v_mul_u32_u24_e32 v188, 0xa0, v188
	v_and_b32_e32 v28, 3, v166
	v_lshl_add_u32 v188, v28, 3, v188
	v_add_u32_e32 v188, s27, v188
	ds_read_b64_tr_b16 v[110:111], v188
	s_lshl_b32 s27, s26, 10
	v_lshlrev_b32_e32 v186, 6, v166
	v_lshl_add_u32 v186, v173, 4, v186
	v_add_u32_e32 v186, s27, v186
	v_add_u32_e32 v186, 0x2800, v186
	v_lshlrev_b32_e32 v28, 2, v173
	v_sub_u32_e32 v28, v166, v28
	v_med3_i32 v66, v28, 0, 4
	v_lshlrev_b32_e64 v66, v66, 1
	v_add_u32_e32 v66, -1, v66
	v_lshlrev_b32_e64 v67, v28, 1
	v_and_b32_e32 v67, 15, v67
	v_bfe_i32 v72, v66, 0, 1
	v_bfe_i32 v73, v66, 1, 1
	v_lshrrev_b32_e32 v72, 16, v72
	v_and_b32_e32 v73, 0xffff0000, v73
	v_or_b32_e32 v68, v72, v73
	v_bfe_i32 v72, v66, 2, 1
	v_bfe_i32 v73, v66, 3, 1
	v_lshrrev_b32_e32 v72, 16, v72
	v_and_b32_e32 v73, 0xffff0000, v73
	v_or_b32_e32 v69, v72, v73
	v_bfe_i32 v72, v67, 0, 1
	v_bfe_i32 v73, v67, 1, 1
	v_lshrrev_b32_e32 v72, 16, v72
	v_and_b32_e32 v73, 0xffff0000, v73
	v_or_b32_e32 v70, v72, v73
	v_bfe_i32 v72, v67, 2, 1
	v_bfe_i32 v73, v67, 3, 1
	v_lshrrev_b32_e32 v72, 16, v72
	v_and_b32_e32 v73, 0xffff0000, v73
	v_or_b32_e32 v71, v72, v73
	v_or_b32_e32 v74, v68, v70
	v_or_b32_e32 v75, v69, v71
	v_not_b32_e32 v74, v74
	v_not_b32_e32 v75, v75
	v_and_b32_e32 v166, 0x3f803f80, v70
	v_and_b32_e32 v173, 0x3f803f80, v71
	v_and_b32_e32 v76, 0x80008000, v68
	v_and_b32_e32 v77, 0x80008000, v69
	s_waitcnt lgkmcnt(1)
	v_and_b32_e32 v26, v26, v68
	v_and_b32_e32 v27, v27, v69
	s_waitcnt lgkmcnt(0)
	v_and_b32_e32 v110, v110, v74
	v_and_b32_e32 v111, v111, v75
	v_xor_b32_e32 v184, v26, v76
	v_xor_b32_e32 v185, v27, v77
	v_or_b32_e32 v184, v184, v166
	v_or_b32_e32 v185, v185, v173
	v_mfma_f32_16x16x16_bf16 v[66:69], v[26:27], v[110:111], 0
	v_mfma_f32_16x16x16_bf16 v[70:73], v[110:111], v[26:27], 0
	s_nop 7
	v_cvt_pk_bf16_f32 v168, v66, v67
	v_cvt_pk_bf16_f32 v169, v68, v69
	v_cvt_pk_bf16_f32 v170, v70, v71
	v_cvt_pk_bf16_f32 v171, v72, v73
	v_or_b32_e32 v26, v168, v166
	v_or_b32_e32 v27, v169, v173
	s_nop 1
	v_mfma_f32_16x16x16_bf16 v[74:77], v[26:27], v[184:185], 0
	v_mfma_f32_16x16x16_bf16 v[66:69], v[170:171], v[168:169], 0
	v_mfma_f32_16x16x16_bf16 v[70:73], v[168:169], v[170:171], 0
	s_nop 6
	v_cvt_pk_bf16_f32 v26, v74, v75
	v_cvt_pk_bf16_f32 v27, v76, v77
	v_cvt_pk_bf16_f32 v110, v66, v67
	v_cvt_pk_bf16_f32 v111, v68, v69
	v_cvt_pk_bf16_f32 v184, v70, v71
	v_cvt_pk_bf16_f32 v185, v72, v73
	s_nop 1
	v_mfma_f32_16x16x16_bf16 v[66:69], v[184:185], v[110:111], 0
	v_or_b32_e32 v184, v184, v166
	v_or_b32_e32 v185, v185, v173
	s_nop 6
	v_cvt_pk_bf16_f32 v110, v66, v67
	v_cvt_pk_bf16_f32 v111, v68, v69
	v_or_b32_e32 v110, v110, v166
	v_or_b32_e32 v111, v111, v173
	s_nop 1
	v_mfma_f32_16x16x16_bf16 v[70:73], v[184:185], v[110:111], 0
	s_nop 7
	v_cvt_pk_bf16_f32 v168, v70, v71
	v_cvt_pk_bf16_f32 v169, v72, v73
	s_nop 1
	v_mfma_f32_16x16x16_bf16 v[66:69], v[168:169], v[26:27], 0
	s_nop 7
	ds_write_b128 v186, v[66:69]
	s_branch .LBB0_391
